# v11 + attention processes each workgroup's long q-block unit first (co-resident workgroups of a head start their long K/V streams together: better L2 sharing)
# baseline (speedup 1.0000x reference)
;   __device__ __forceinline__ bool next(int i,AttnUnit&u)const{
;     if(grid!=256){ const int k=i*grid+blk; if(k>=16*NQB)return false; u.bh=k/NQB; u.qb=NQB-1-(k%NQB); return true; }
;     if(i>=2)return false; const int s=vcu&15; u.bh=vcu>>4; u.qb=(i==0)?s:31-s; return true; }
.LBB0_578:
	s_andn2_b64 vcc, exec, s[12:13]
	s_cbranch_vccnz .LBB0_582
	s_cmp_gt_u32 s82, 1
	s_mov_b64 s[10:11], 0
	s_cbranch_scc1 .LBB0_581
	s_cmp_eq_u32 s82, 0
	s_cselect_b32 s4, s97, s96
	s_mov_b64 s[10:11], -1
	s_mov_b32 s5, s76
